# v62 + grid barrier release polls pipelined (3 poll rounds in flight, results in dead registers, no drain after release)
# speedup vs baseline: 1.0029x; 1.0029x over previous
; __device__ __forceinline__ unsigned xb_ld(unsigned* p)              { return __hip_atomic_load(p, __ATOMIC_RELAXED, __HIP_MEMORY_SCOPE_AGENT); }
; __device__ __forceinline__ unsigned xb_add(unsigned* p, unsigned v) { return __hip_atomic_fetch_add(p, v, __ATOMIC_RELAXED, __HIP_MEMORY_SCOPE_AGENT); }
; #define XB_SPIN(cond, bar) do { unsigned _sp = 0; while (cond) { __builtin_amdgcn_s_sleep(1); \
;     if ((++_sp & 255u) == 0u) { if (xb_ld(&(bar)[XB_TMO])) break; if (_sp > XB_SPIN_CAP) { atomicAdd(&(bar)[XB_TMO], 1u); break; } } } } while (0)
; __device__ __forceinline__ void xcd_barrier(const XcdBarrier& b) {
;     ...
;         const unsigned old = xb_add(&bar[XB_XSUB(b.x)], 1u);
;         const unsigned gen = old / nloc;
;         if (old + 1u == (gen + 1u) * nloc) {
;             __builtin_amdgcn_fence(__ATOMIC_RELEASE, "agent");
;             asm volatile("s_waitcnt vmcnt(0)" ::: "memory");
;             asm volatile("buffer_inv sc1" ::: "memory");
;             const unsigned og = xb_add(&bar[XB_TOP], 1u);
;             const unsigned tg = og / nx;
;             const bool last_top = (og + 1u == (tg + 1u) * nx);
;             if (last_top) (void)__hip_atomic_fetch_add(&bar[XB_TOPGEN], 1u, __ATOMIC_RELAXED, __HIP_MEMORY_SCOPE_AGENT);
;             asm volatile("s_waitcnt vmcnt(0)" ::: "memory");
;             (void)__hip_atomic_fetch_add(&bar[XB_XGEN(b.x)], 1u, __ATOMIC_RELAXED, __HIP_MEMORY_SCOPE_AGENT);
;             if (!last_top) XB_SPIN(xb_ld(&bar[XB_TOPGEN]) == tg, bar);
;         } else {
;             asm volatile("buffer_inv sc1" ::: "memory");
;             { unsigned _sp = 0; for (;;) { const unsigned a_ = xb_ld(&bar[XB_TOPGEN]), c_ = xb_ld(&bar[XB_XGEN(b.x)]); if (a_ != gen && c_ != gen) break; __builtin_amdgcn_s_sleep(1);
;                 if ((++_sp & 255u) == 0u) { if (xb_ld(&bar[XB_TMO])) break; if (_sp > XB_SPIN_CAP) { atomicAdd(&bar[XB_TMO], 1u); break; } } } }
.LBB0_90:
	s_or_b64 exec, exec, s[10:11]
	v_cvt_f32_u32_e32 v5, v3
	s_waitcnt vmcnt(0)
	v_readfirstlane_b32 s0, v4
	v_sub_u32_e32 v4, 0, v3
	v_rcp_iflag_f32_e32 v5, v5
	v_add_u32_e32 v6, s0, v2
	v_mul_f32_e32 v5, 0x4f7ffffe, v5
	v_cvt_u32_f32_e32 v5, v5
	v_mul_lo_u32 v2, v4, v5
	v_mul_hi_u32 v2, v5, v2
	v_add_u32_e32 v2, v5, v2
	v_mul_hi_u32 v2, v6, v2
	v_mul_lo_u32 v4, v2, v3
	v_sub_u32_e32 v4, v6, v4
	v_add_u32_e32 v5, 1, v2
	v_cmp_ge_u32_e32 vcc, v4, v3
	s_nop 1
	v_cndmask_b32_e32 v2, v2, v5, vcc
	v_sub_u32_e32 v5, v4, v3
	v_cndmask_b32_e32 v4, v4, v5, vcc
	v_add_u32_e32 v5, 1, v2
	v_cmp_ge_u32_e32 vcc, v4, v3
	v_add_u32_e32 v4, 1, v6
	s_nop 0
	v_cndmask_b32_e32 v2, v2, v5, vcc
	v_mul_lo_u32 v5, v3, v2
	v_add_u32_e32 v3, v5, v3
	v_cmp_ne_u32_e32 vcc, v4, v3
	s_and_saveexec_b64 s[0:1], vcc
	s_xor_b64 s[10:11], exec, s[0:1]
	s_cbranch_execz .LBB0_104
	buffer_inv sc1
	s_waitcnt lgkmcnt(0)
	v_mov_b32_e32 v1, 0x7000
	v_mov_b32_e32 v3, 0x2000
	global_load_dword v1, v1, s[50:51] offset:1280 sc1
	s_add_u32 s16, s50, 0x7500
	global_load_dword v3, v3, s[8:9] offset:1024 sc1
	s_addc_u32 s17, s51, 0
	s_add_u32 s18, s8, 0x2400
	s_addc_u32 s19, s9, 0
	s_waitcnt vmcnt(1)
	v_cmp_eq_u32_e32 vcc, v1, v2
	s_waitcnt vmcnt(0)
	v_cmp_eq_u32_e64 s[0:1], v3, v2
	s_or_b64 s[0:1], vcc, s[0:1]
	s_and_b64 s[0:1], s[0:1], exec
	s_cbranch_scc0 .LBB0_103
	v_mov_b32_e32 v250, 0
	global_load_dword v244, v250, s[16:17] sc1
	global_load_dword v245, v250, s[18:19] sc1
	s_sleep 14
	global_load_dword v246, v250, s[16:17] sc1
	global_load_dword v247, v250, s[18:19] sc1
	s_sleep 14
	global_load_dword v248, v250, s[16:17] sc1
	global_load_dword v249, v250, s[18:19] sc1
my_pl_0:
	s_waitcnt vmcnt(4)
	v_cmp_ne_u32_e32 vcc, v244, v2
	v_cmp_ne_u32_e64 s[0:1], v245, v2
	s_and_b64 s[0:1], vcc, s[0:1]
	s_and_b64 s[0:1], s[0:1], exec
	s_cbranch_scc1 .LBB0_103
	global_load_dword v244, v250, s[16:17] sc1
	global_load_dword v245, v250, s[18:19] sc1
	s_waitcnt vmcnt(4)
	v_cmp_ne_u32_e32 vcc, v246, v2
	v_cmp_ne_u32_e64 s[0:1], v247, v2
	s_and_b64 s[0:1], vcc, s[0:1]
	s_and_b64 s[0:1], s[0:1], exec
	s_cbranch_scc1 .LBB0_103
	global_load_dword v246, v250, s[16:17] sc1
	global_load_dword v247, v250, s[18:19] sc1
	s_waitcnt vmcnt(4)
	v_cmp_ne_u32_e32 vcc, v248, v2
	v_cmp_ne_u32_e64 s[0:1], v249, v2
	s_and_b64 s[0:1], vcc, s[0:1]
	s_and_b64 s[0:1], s[0:1], exec
	s_cbranch_scc1 .LBB0_103
	global_load_dword v248, v250, s[16:17] sc1
	global_load_dword v249, v250, s[18:19] sc1
	s_branch my_pl_0
.LBB0_103:
.LBB0_104:
	s_andn2_saveexec_b64 s[0:1], s[10:11]
	s_cbranch_execz .LBB0_126
	s_mov_b64 s[0:1], exec
	buffer_wbl2 sc1
	s_waitcnt vmcnt(0) lgkmcnt(0)
	s_waitcnt vmcnt(0)
	buffer_inv sc1
	v_mbcnt_lo_u32_b32 v2, s0, 0
	v_mbcnt_hi_u32_b32 v2, s1, v2
	v_cmp_eq_u32_e32 vcc, 0, v2
	s_and_saveexec_b64 s[10:11], vcc
	s_cbranch_execz .LBB0_107
	s_bcnt1_i32_b64 s0, s[0:1]
	v_mov_b32_e32 v3, 0x7000
	v_mov_b32_e32 v4, s0
	global_atomic_add v3, v3, v4, s[50:51] offset:1024 sc0

; __device__ __forceinline__ unsigned xb_ld(unsigned* p)              { return __hip_atomic_load(p, __ATOMIC_RELAXED, __HIP_MEMORY_SCOPE_AGENT); }
; __device__ __forceinline__ unsigned xb_add(unsigned* p, unsigned v) { return __hip_atomic_fetch_add(p, v, __ATOMIC_RELAXED, __HIP_MEMORY_SCOPE_AGENT); }
; #define XB_SPIN(cond, bar) do { unsigned _sp = 0; while (cond) { __builtin_amdgcn_s_sleep(1); \
;     if ((++_sp & 255u) == 0u) { if (xb_ld(&(bar)[XB_TMO])) break; if (_sp > XB_SPIN_CAP) { atomicAdd(&(bar)[XB_TMO], 1u); break; } } } } while (0)
; __device__ __forceinline__ void xcd_barrier(const XcdBarrier& b) {
;     ...
;             const unsigned og = xb_add(&bar[XB_TOP], 1u);
;             const unsigned tg = og / nx;
;             const bool last_top = (og + 1u == (tg + 1u) * nx);
;             if (last_top) (void)__hip_atomic_fetch_add(&bar[XB_TOPGEN], 1u, __ATOMIC_RELAXED, __HIP_MEMORY_SCOPE_AGENT);
;             asm volatile("s_waitcnt vmcnt(0)" ::: "memory");
;             (void)__hip_atomic_fetch_add(&bar[XB_XGEN(b.x)], 1u, __ATOMIC_RELAXED, __HIP_MEMORY_SCOPE_AGENT);
;             if (!last_top) XB_SPIN(xb_ld(&bar[XB_TOPGEN]) == tg, bar);
.LBB0_112:
	s_or_b64 exec, exec, s[12:13]
	s_and_saveexec_b64 s[0:1], vcc
	s_cbranch_execz .LBB0_125
	v_mov_b32_e32 v1, 0x7000
	global_load_dword v1, v1, s[50:51] offset:1280 sc1
	s_add_u32 s10, s50, 0x7500
	s_addc_u32 s11, s51, 0
	s_waitcnt vmcnt(0)
	v_cmp_eq_u32_e32 vcc, v1, v2
	s_and_b64 vcc, vcc, exec
	s_cbranch_vccz .LBB0_125
	v_mov_b32_e32 v250, 0
	global_load_dword v244, v250, s[10:11] sc1
	s_sleep 14
	global_load_dword v246, v250, s[10:11] sc1
	s_sleep 14
	global_load_dword v248, v250, s[10:11] sc1
my_ll_0:
	s_waitcnt vmcnt(2)
	v_cmp_ne_u32_e32 vcc, v244, v2
	s_and_b64 vcc, vcc, exec
	s_cbranch_vccnz .LBB0_125
	global_load_dword v244, v250, s[10:11] sc1
	s_waitcnt vmcnt(2)
	v_cmp_ne_u32_e32 vcc, v246, v2
	s_and_b64 vcc, vcc, exec
	s_cbranch_vccnz .LBB0_125
	global_load_dword v246, v250, s[10:11] sc1
	s_waitcnt vmcnt(2)
	v_cmp_ne_u32_e32 vcc, v248, v2
	s_and_b64 vcc, vcc, exec
	s_cbranch_vccnz .LBB0_125
	global_load_dword v248, v250, s[10:11] sc1
	s_branch my_ll_0

; __device__ __forceinline__ unsigned xb_ld(unsigned* p)              { return __hip_atomic_load(p, __ATOMIC_RELAXED, __HIP_MEMORY_SCOPE_AGENT); }
; __device__ __forceinline__ unsigned xb_add(unsigned* p, unsigned v) { return __hip_atomic_fetch_add(p, v, __ATOMIC_RELAXED, __HIP_MEMORY_SCOPE_AGENT); }
; #define XB_SPIN(cond, bar) do { unsigned _sp = 0; while (cond) { __builtin_amdgcn_s_sleep(1); \
;     if ((++_sp & 255u) == 0u) { if (xb_ld(&(bar)[XB_TMO])) break; if (_sp > XB_SPIN_CAP) { atomicAdd(&(bar)[XB_TMO], 1u); break; } } } } while (0)
; __device__ __forceinline__ void xcd_barrier(const XcdBarrier& b) {
;     ...
;         const unsigned old = xb_add(&bar[XB_XSUB(b.x)], 1u);
;         const unsigned gen = old / nloc;
;         if (old + 1u == (gen + 1u) * nloc) {
;             __builtin_amdgcn_fence(__ATOMIC_RELEASE, "agent");
;             asm volatile("s_waitcnt vmcnt(0)" ::: "memory");
;             asm volatile("buffer_inv sc1" ::: "memory");
;             const unsigned og = xb_add(&bar[XB_TOP], 1u);
;             const unsigned tg = og / nx;
;             const bool last_top = (og + 1u == (tg + 1u) * nx);
;             if (last_top) (void)__hip_atomic_fetch_add(&bar[XB_TOPGEN], 1u, __ATOMIC_RELAXED, __HIP_MEMORY_SCOPE_AGENT);
;             asm volatile("s_waitcnt vmcnt(0)" ::: "memory");
;             (void)__hip_atomic_fetch_add(&bar[XB_XGEN(b.x)], 1u, __ATOMIC_RELAXED, __HIP_MEMORY_SCOPE_AGENT);
;             if (!last_top) XB_SPIN(xb_ld(&bar[XB_TOPGEN]) == tg, bar);
;         } else {
;             asm volatile("buffer_inv sc1" ::: "memory");
;             { unsigned _sp = 0; for (;;) { const unsigned a_ = xb_ld(&bar[XB_TOPGEN]), c_ = xb_ld(&bar[XB_XGEN(b.x)]); if (a_ != gen && c_ != gen) break; __builtin_amdgcn_s_sleep(1);
;                 if ((++_sp & 255u) == 0u) { if (xb_ld(&bar[XB_TMO])) break; if (_sp > XB_SPIN_CAP) { atomicAdd(&bar[XB_TMO], 1u); break; } } } }
.LBB0_237:
	s_or_b64 exec, exec, s[10:11]
	v_cvt_f32_u32_e32 v6, v4
	s_waitcnt vmcnt(0)
	v_readfirstlane_b32 s0, v5
	v_sub_u32_e32 v5, 0, v4
	v_rcp_iflag_f32_e32 v6, v6
	v_add_u32_e32 v7, s0, v3
	v_mul_f32_e32 v6, 0x4f7ffffe, v6
	v_cvt_u32_f32_e32 v6, v6
	v_mul_lo_u32 v3, v5, v6
	v_mul_hi_u32 v3, v6, v3
	v_add_u32_e32 v3, v6, v3
	v_mul_hi_u32 v3, v7, v3
	v_mul_lo_u32 v5, v3, v4
	v_sub_u32_e32 v5, v7, v5
	v_add_u32_e32 v6, 1, v3
	v_cmp_ge_u32_e32 vcc, v5, v4
	s_nop 1
	v_cndmask_b32_e32 v3, v3, v6, vcc
	v_sub_u32_e32 v6, v5, v4
	v_cndmask_b32_e32 v5, v5, v6, vcc
	v_add_u32_e32 v6, 1, v3
	v_cmp_ge_u32_e32 vcc, v5, v4
	v_add_u32_e32 v5, 1, v7
	s_nop 0
	v_cndmask_b32_e32 v3, v3, v6, vcc
	v_mul_lo_u32 v6, v4, v3
	v_add_u32_e32 v4, v6, v4
	v_cmp_ne_u32_e32 vcc, v5, v4
	s_and_saveexec_b64 s[0:1], vcc
	s_xor_b64 s[10:11], exec, s[0:1]
	s_cbranch_execz .LBB0_251
	buffer_inv sc1
	s_waitcnt lgkmcnt(0)
	v_mov_b32_e32 v2, 0x7000
	v_mov_b32_e32 v4, 0x2000
	global_load_dword v2, v2, s[50:51] offset:1280 sc1
	s_add_u32 s16, s50, 0x7500
	global_load_dword v4, v4, s[8:9] offset:1024 sc1
	s_addc_u32 s17, s51, 0
	s_add_u32 s18, s8, 0x2400
	s_addc_u32 s19, s9, 0
	s_waitcnt vmcnt(1)
	v_cmp_eq_u32_e32 vcc, v2, v3
	s_waitcnt vmcnt(0)
	v_cmp_eq_u32_e64 s[0:1], v4, v3
	s_or_b64 s[0:1], vcc, s[0:1]
	s_and_b64 s[0:1], s[0:1], exec
	s_cbranch_scc0 .LBB0_250
	v_mov_b32_e32 v250, 0
	global_load_dword v244, v250, s[16:17] sc1
	global_load_dword v245, v250, s[18:19] sc1
	s_sleep 14
	global_load_dword v246, v250, s[16:17] sc1
	global_load_dword v247, v250, s[18:19] sc1
	s_sleep 14
	global_load_dword v248, v250, s[16:17] sc1
	global_load_dword v249, v250, s[18:19] sc1
my_pl_1:
	s_waitcnt vmcnt(4)
	v_cmp_ne_u32_e32 vcc, v244, v3
	v_cmp_ne_u32_e64 s[0:1], v245, v3
	s_and_b64 s[0:1], vcc, s[0:1]
	s_and_b64 s[0:1], s[0:1], exec
	s_cbranch_scc1 .LBB0_250
	global_load_dword v244, v250, s[16:17] sc1
	global_load_dword v245, v250, s[18:19] sc1
	s_waitcnt vmcnt(4)
	v_cmp_ne_u32_e32 vcc, v246, v3
	v_cmp_ne_u32_e64 s[0:1], v247, v3
	s_and_b64 s[0:1], vcc, s[0:1]
	s_and_b64 s[0:1], s[0:1], exec
	s_cbranch_scc1 .LBB0_250
	global_load_dword v246, v250, s[16:17] sc1
	global_load_dword v247, v250, s[18:19] sc1
	s_waitcnt vmcnt(4)
	v_cmp_ne_u32_e32 vcc, v248, v3
	v_cmp_ne_u32_e64 s[0:1], v249, v3
	s_and_b64 s[0:1], vcc, s[0:1]
	s_and_b64 s[0:1], s[0:1], exec
	s_cbranch_scc1 .LBB0_250
	global_load_dword v248, v250, s[16:17] sc1
	global_load_dword v249, v250, s[18:19] sc1
	s_branch my_pl_1
.LBB0_250:
.LBB0_251:
	s_andn2_saveexec_b64 s[0:1], s[10:11]
	s_cbranch_execz .LBB0_273
	s_mov_b64 s[0:1], exec
	buffer_wbl2 sc1
	s_waitcnt vmcnt(0) lgkmcnt(0)
	s_waitcnt vmcnt(0)
	buffer_inv sc1
	v_mbcnt_lo_u32_b32 v3, s0, 0
	v_mbcnt_hi_u32_b32 v3, s1, v3
	v_cmp_eq_u32_e32 vcc, 0, v3
	s_and_saveexec_b64 s[10:11], vcc
	s_cbranch_execz .LBB0_254
	s_bcnt1_i32_b64 s0, s[0:1]
	v_mov_b32_e32 v4, 0x7000
	v_mov_b32_e32 v5, s0
	global_atomic_add v4, v4, v5, s[50:51] offset:1024 sc0

; __device__ __forceinline__ unsigned xb_ld(unsigned* p)              { return __hip_atomic_load(p, __ATOMIC_RELAXED, __HIP_MEMORY_SCOPE_AGENT); }
; __device__ __forceinline__ unsigned xb_add(unsigned* p, unsigned v) { return __hip_atomic_fetch_add(p, v, __ATOMIC_RELAXED, __HIP_MEMORY_SCOPE_AGENT); }
; #define XB_SPIN(cond, bar) do { unsigned _sp = 0; while (cond) { __builtin_amdgcn_s_sleep(1); \
;     if ((++_sp & 255u) == 0u) { if (xb_ld(&(bar)[XB_TMO])) break; if (_sp > XB_SPIN_CAP) { atomicAdd(&(bar)[XB_TMO], 1u); break; } } } } while (0)
; __device__ __forceinline__ void xcd_barrier(const XcdBarrier& b) {
;     ...
;             const unsigned og = xb_add(&bar[XB_TOP], 1u);
;             const unsigned tg = og / nx;
;             const bool last_top = (og + 1u == (tg + 1u) * nx);
;             if (last_top) (void)__hip_atomic_fetch_add(&bar[XB_TOPGEN], 1u, __ATOMIC_RELAXED, __HIP_MEMORY_SCOPE_AGENT);
;             asm volatile("s_waitcnt vmcnt(0)" ::: "memory");
;             (void)__hip_atomic_fetch_add(&bar[XB_XGEN(b.x)], 1u, __ATOMIC_RELAXED, __HIP_MEMORY_SCOPE_AGENT);
;             if (!last_top) XB_SPIN(xb_ld(&bar[XB_TOPGEN]) == tg, bar);
.LBB0_259:
	s_or_b64 exec, exec, s[12:13]
	s_and_saveexec_b64 s[0:1], vcc
	s_cbranch_execz .LBB0_272
	v_mov_b32_e32 v2, 0x7000
	global_load_dword v2, v2, s[50:51] offset:1280 sc1
	s_add_u32 s10, s50, 0x7500
	s_addc_u32 s11, s51, 0
	s_waitcnt vmcnt(0)
	v_cmp_eq_u32_e32 vcc, v2, v3
	s_and_b64 vcc, vcc, exec
	s_cbranch_vccz .LBB0_272
	v_mov_b32_e32 v250, 0
	global_load_dword v244, v250, s[10:11] sc1
	s_sleep 14
	global_load_dword v246, v250, s[10:11] sc1
	s_sleep 14
	global_load_dword v248, v250, s[10:11] sc1
my_ll_1:
	s_waitcnt vmcnt(2)
	v_cmp_ne_u32_e32 vcc, v244, v3
	s_and_b64 vcc, vcc, exec
	s_cbranch_vccnz .LBB0_272
	global_load_dword v244, v250, s[10:11] sc1
	s_waitcnt vmcnt(2)
	v_cmp_ne_u32_e32 vcc, v246, v3
	s_and_b64 vcc, vcc, exec
	s_cbranch_vccnz .LBB0_272
	global_load_dword v246, v250, s[10:11] sc1
	s_waitcnt vmcnt(2)
	v_cmp_ne_u32_e32 vcc, v248, v3
	s_and_b64 vcc, vcc, exec
	s_cbranch_vccnz .LBB0_272
	global_load_dword v248, v250, s[10:11] sc1
	s_branch my_ll_1

; __device__ __forceinline__ unsigned xb_ld(unsigned* p)              { return __hip_atomic_load(p, __ATOMIC_RELAXED, __HIP_MEMORY_SCOPE_AGENT); }
; __device__ __forceinline__ void xcd_barrier(const XcdBarrier& b) {
;     ...
;             { unsigned _sp = 0; for (;;) { const unsigned a_ = xb_ld(&bar[XB_TOPGEN]), c_ = xb_ld(&bar[XB_XGEN(b.x)]); if (a_ != gen && c_ != gen) break; __builtin_amdgcn_s_sleep(1);
;                 if ((++_sp & 255u) == 0u) { if (xb_ld(&bar[XB_TMO])) break; if (_sp > XB_SPIN_CAP) { atomicAdd(&bar[XB_TMO], 1u); break; } } } }
my_pl_2:
	s_waitcnt vmcnt(4)
	v_cmp_ne_u32_e32 vcc, v244, v3
	v_cmp_ne_u32_e64 s[0:1], v245, v3
	s_and_b64 s[0:1], vcc, s[0:1]
	s_and_b64 s[0:1], s[0:1], exec
	s_cbranch_scc1 .LBB0_583
	global_load_dword v244, v250, s[16:17] sc1
	global_load_dword v245, v250, s[18:19] sc1
	s_waitcnt vmcnt(4)
	v_cmp_ne_u32_e32 vcc, v246, v3
	v_cmp_ne_u32_e64 s[0:1], v247, v3
	s_and_b64 s[0:1], vcc, s[0:1]
	s_and_b64 s[0:1], s[0:1], exec
	s_cbranch_scc1 .LBB0_583
	global_load_dword v246, v250, s[16:17] sc1
	global_load_dword v247, v250, s[18:19] sc1
	s_waitcnt vmcnt(4)
	v_cmp_ne_u32_e32 vcc, v248, v3
	v_cmp_ne_u32_e64 s[0:1], v249, v3
	s_and_b64 s[0:1], vcc, s[0:1]
	s_and_b64 s[0:1], s[0:1], exec
	s_cbranch_scc1 .LBB0_583
	global_load_dword v248, v250, s[16:17] sc1
	global_load_dword v249, v250, s[18:19] sc1
	s_branch my_pl_2

; __device__ __forceinline__ unsigned xb_ld(unsigned* p)              { return __hip_atomic_load(p, __ATOMIC_RELAXED, __HIP_MEMORY_SCOPE_AGENT); }
; #define XB_SPIN(cond, bar) do { unsigned _sp = 0; while (cond) { __builtin_amdgcn_s_sleep(1); \
;     if ((++_sp & 255u) == 0u) { if (xb_ld(&(bar)[XB_TMO])) break; if (_sp > XB_SPIN_CAP) { atomicAdd(&(bar)[XB_TMO], 1u); break; } } } } while (0)
; __device__ __forceinline__ void xcd_barrier(const XcdBarrier& b) {
;     ...
;             if (!last_top) XB_SPIN(xb_ld(&bar[XB_TOPGEN]) == tg, bar);
my_ll_2:
	s_waitcnt vmcnt(2)
	v_cmp_ne_u32_e32 vcc, v244, v3
	s_and_b64 vcc, vcc, exec
	s_cbranch_vccnz .LBB0_605
	global_load_dword v244, v250, s[10:11] sc1
	s_waitcnt vmcnt(2)
	v_cmp_ne_u32_e32 vcc, v246, v3
	s_and_b64 vcc, vcc, exec
	s_cbranch_vccnz .LBB0_605
	global_load_dword v246, v250, s[10:11] sc1
	s_waitcnt vmcnt(2)
	v_cmp_ne_u32_e32 vcc, v248, v3
	s_and_b64 vcc, vcc, exec
	s_cbranch_vccnz .LBB0_605
	global_load_dword v248, v250, s[10:11] sc1
	s_branch my_ll_2

; __device__ __forceinline__ unsigned xb_ld(unsigned* p)              { return __hip_atomic_load(p, __ATOMIC_RELAXED, __HIP_MEMORY_SCOPE_AGENT); }
; __device__ __forceinline__ void xcd_barrier(const XcdBarrier& b) {
;     ...
;             { unsigned _sp = 0; for (;;) { const unsigned a_ = xb_ld(&bar[XB_TOPGEN]), c_ = xb_ld(&bar[XB_XGEN(b.x)]); if (a_ != gen && c_ != gen) break; __builtin_amdgcn_s_sleep(1);
;                 if ((++_sp & 255u) == 0u) { if (xb_ld(&bar[XB_TMO])) break; if (_sp > XB_SPIN_CAP) { atomicAdd(&bar[XB_TMO], 1u); break; } } } }
my_pl_3:
	s_waitcnt vmcnt(4)
	v_cmp_ne_u32_e32 vcc, v244, v3
	v_cmp_ne_u32_e64 s[0:1], v245, v3
	s_and_b64 s[0:1], vcc, s[0:1]
	s_and_b64 s[0:1], s[0:1], exec
	s_cbranch_scc1 .LBB0_643
	global_load_dword v244, v250, s[16:17] sc1
	global_load_dword v245, v250, s[18:19] sc1
	s_waitcnt vmcnt(4)
	v_cmp_ne_u32_e32 vcc, v246, v3
	v_cmp_ne_u32_e64 s[0:1], v247, v3
	s_and_b64 s[0:1], vcc, s[0:1]
	s_and_b64 s[0:1], s[0:1], exec
	s_cbranch_scc1 .LBB0_643
	global_load_dword v246, v250, s[16:17] sc1
	global_load_dword v247, v250, s[18:19] sc1
	s_waitcnt vmcnt(4)
	v_cmp_ne_u32_e32 vcc, v248, v3
	v_cmp_ne_u32_e64 s[0:1], v249, v3
	s_and_b64 s[0:1], vcc, s[0:1]
	s_and_b64 s[0:1], s[0:1], exec
	s_cbranch_scc1 .LBB0_643
	global_load_dword v248, v250, s[16:17] sc1
	global_load_dword v249, v250, s[18:19] sc1
	s_branch my_pl_3

; __device__ __forceinline__ unsigned xb_ld(unsigned* p)              { return __hip_atomic_load(p, __ATOMIC_RELAXED, __HIP_MEMORY_SCOPE_AGENT); }
; #define XB_SPIN(cond, bar) do { unsigned _sp = 0; while (cond) { __builtin_amdgcn_s_sleep(1); \
;     if ((++_sp & 255u) == 0u) { if (xb_ld(&(bar)[XB_TMO])) break; if (_sp > XB_SPIN_CAP) { atomicAdd(&(bar)[XB_TMO], 1u); break; } } } } while (0)
; __device__ __forceinline__ void xcd_barrier(const XcdBarrier& b) {
;     ...
;             if (!last_top) XB_SPIN(xb_ld(&bar[XB_TOPGEN]) == tg, bar);
my_ll_3:
	s_waitcnt vmcnt(2)
	v_cmp_ne_u32_e32 vcc, v244, v3
	s_and_b64 vcc, vcc, exec
	s_cbranch_vccnz .LBB0_665
	global_load_dword v244, v250, s[10:11] sc1
	s_waitcnt vmcnt(2)
	v_cmp_ne_u32_e32 vcc, v246, v3
	s_and_b64 vcc, vcc, exec
	s_cbranch_vccnz .LBB0_665
	global_load_dword v246, v250, s[10:11] sc1
	s_waitcnt vmcnt(2)
	v_cmp_ne_u32_e32 vcc, v248, v3
	s_and_b64 vcc, vcc, exec
	s_cbranch_vccnz .LBB0_665
	global_load_dword v248, v250, s[10:11] sc1
	s_branch my_ll_3

; __device__ __forceinline__ unsigned xb_ld(unsigned* p)              { return __hip_atomic_load(p, __ATOMIC_RELAXED, __HIP_MEMORY_SCOPE_AGENT); }
; __device__ __forceinline__ unsigned xb_add(unsigned* p, unsigned v) { return __hip_atomic_fetch_add(p, v, __ATOMIC_RELAXED, __HIP_MEMORY_SCOPE_AGENT); }
; #define XB_SPIN(cond, bar) do { unsigned _sp = 0; while (cond) { __builtin_amdgcn_s_sleep(1); \
;     if ((++_sp & 255u) == 0u) { if (xb_ld(&(bar)[XB_TMO])) break; if (_sp > XB_SPIN_CAP) { atomicAdd(&(bar)[XB_TMO], 1u); break; } } } } while (0)
; __device__ __forceinline__ void xcd_barrier(const XcdBarrier& b) {
;     ...
;         const unsigned old = xb_add(&bar[XB_XSUB(b.x)], 1u);
;         const unsigned gen = old / nloc;
;         if (old + 1u == (gen + 1u) * nloc) {
;             __builtin_amdgcn_fence(__ATOMIC_RELEASE, "agent");
;             asm volatile("s_waitcnt vmcnt(0)" ::: "memory");
;             asm volatile("buffer_inv sc1" ::: "memory");
;             const unsigned og = xb_add(&bar[XB_TOP], 1u);
;             const unsigned tg = og / nx;
;             const bool last_top = (og + 1u == (tg + 1u) * nx);
;             if (last_top) (void)__hip_atomic_fetch_add(&bar[XB_TOPGEN], 1u, __ATOMIC_RELAXED, __HIP_MEMORY_SCOPE_AGENT);
;             asm volatile("s_waitcnt vmcnt(0)" ::: "memory");
;             (void)__hip_atomic_fetch_add(&bar[XB_XGEN(b.x)], 1u, __ATOMIC_RELAXED, __HIP_MEMORY_SCOPE_AGENT);
;             if (!last_top) XB_SPIN(xb_ld(&bar[XB_TOPGEN]) == tg, bar);
;         } else {
;             asm volatile("buffer_inv sc1" ::: "memory");
;             { unsigned _sp = 0; for (;;) { const unsigned a_ = xb_ld(&bar[XB_TOPGEN]), c_ = xb_ld(&bar[XB_XGEN(b.x)]); if (a_ != gen && c_ != gen) break; __builtin_amdgcn_s_sleep(1);
;                 if ((++_sp & 255u) == 0u) { if (xb_ld(&bar[XB_TMO])) break; if (_sp > XB_SPIN_CAP) { atomicAdd(&bar[XB_TMO], 1u); break; } } } }
.LBB0_720:
	s_or_b64 exec, exec, s[12:13]
	v_cvt_f32_u32_e32 v6, v4
	s_waitcnt vmcnt(0)
	v_readfirstlane_b32 s0, v5
	v_sub_u32_e32 v5, 0, v4
	v_rcp_iflag_f32_e32 v6, v6
	v_add_u32_e32 v7, s0, v3
	v_mul_f32_e32 v6, 0x4f7ffffe, v6
	v_cvt_u32_f32_e32 v6, v6
	v_mul_lo_u32 v3, v5, v6
	v_mul_hi_u32 v3, v6, v3
	v_add_u32_e32 v3, v6, v3
	v_mul_hi_u32 v3, v7, v3
	v_mul_lo_u32 v5, v3, v4
	v_sub_u32_e32 v5, v7, v5
	v_add_u32_e32 v6, 1, v3
	v_cmp_ge_u32_e32 vcc, v5, v4
	s_nop 1
	v_cndmask_b32_e32 v3, v3, v6, vcc
	v_sub_u32_e32 v6, v5, v4
	v_cndmask_b32_e32 v5, v5, v6, vcc
	v_add_u32_e32 v6, 1, v3
	v_cmp_ge_u32_e32 vcc, v5, v4
	v_add_u32_e32 v5, 1, v7
	s_nop 0
	v_cndmask_b32_e32 v3, v3, v6, vcc
	v_mul_lo_u32 v6, v4, v3
	v_add_u32_e32 v4, v6, v4
	v_cmp_ne_u32_e32 vcc, v5, v4
	s_and_saveexec_b64 s[0:1], vcc
	s_xor_b64 s[12:13], exec, s[0:1]
	s_cbranch_execz .LBB0_734
	buffer_inv sc1
	s_waitcnt lgkmcnt(0)
	v_mov_b32_e32 v2, 0x7000
	v_mov_b32_e32 v4, 0x2000
	global_load_dword v2, v2, s[50:51] offset:1280 sc1
	s_add_u32 s18, s50, 0x7500
	global_load_dword v4, v4, s[10:11] offset:1024 sc1
	s_addc_u32 s19, s51, 0
	s_add_u32 s20, s10, 0x2400
	s_addc_u32 s21, s11, 0
	s_waitcnt vmcnt(1)
	v_cmp_eq_u32_e32 vcc, v2, v3
	s_waitcnt vmcnt(0)
	v_cmp_eq_u32_e64 s[0:1], v4, v3
	s_or_b64 s[0:1], vcc, s[0:1]
	s_and_b64 s[0:1], s[0:1], exec
	s_cbranch_scc0 .LBB0_733
	v_mov_b32_e32 v250, 0
	global_load_dword v244, v250, s[18:19] sc1
	global_load_dword v245, v250, s[20:21] sc1
	s_sleep 14
	global_load_dword v246, v250, s[18:19] sc1
	global_load_dword v247, v250, s[20:21] sc1
	s_sleep 14
	global_load_dword v248, v250, s[18:19] sc1
	global_load_dword v249, v250, s[20:21] sc1
my_pl_4:
	s_waitcnt vmcnt(4)
	v_cmp_ne_u32_e32 vcc, v244, v3
	v_cmp_ne_u32_e64 s[0:1], v245, v3
	s_and_b64 s[0:1], vcc, s[0:1]
	s_and_b64 s[0:1], s[0:1], exec
	s_cbranch_scc1 .LBB0_733
	global_load_dword v244, v250, s[18:19] sc1
	global_load_dword v245, v250, s[20:21] sc1
	s_waitcnt vmcnt(4)
	v_cmp_ne_u32_e32 vcc, v246, v3
	v_cmp_ne_u32_e64 s[0:1], v247, v3
	s_and_b64 s[0:1], vcc, s[0:1]
	s_and_b64 s[0:1], s[0:1], exec
	s_cbranch_scc1 .LBB0_733
	global_load_dword v246, v250, s[18:19] sc1
	global_load_dword v247, v250, s[20:21] sc1
	s_waitcnt vmcnt(4)
	v_cmp_ne_u32_e32 vcc, v248, v3
	v_cmp_ne_u32_e64 s[0:1], v249, v3
	s_and_b64 s[0:1], vcc, s[0:1]
	s_and_b64 s[0:1], s[0:1], exec
	s_cbranch_scc1 .LBB0_733
	global_load_dword v248, v250, s[18:19] sc1
	global_load_dword v249, v250, s[20:21] sc1
	s_branch my_pl_4
.LBB0_733:
.LBB0_734:
	s_andn2_saveexec_b64 s[0:1], s[12:13]
	s_cbranch_execz .LBB0_756
	s_mov_b64 s[0:1], exec
	buffer_wbl2 sc1
	s_waitcnt vmcnt(0) lgkmcnt(0)
	s_waitcnt vmcnt(0)
	buffer_inv sc1
	v_mbcnt_lo_u32_b32 v3, s0, 0
	v_mbcnt_hi_u32_b32 v3, s1, v3
	v_cmp_eq_u32_e32 vcc, 0, v3
	s_and_saveexec_b64 s[12:13], vcc
	s_cbranch_execz .LBB0_737
	s_bcnt1_i32_b64 s0, s[0:1]
	v_mov_b32_e32 v4, 0x7000
	v_mov_b32_e32 v5, s0
	global_atomic_add v4, v4, v5, s[50:51] offset:1024 sc0

; __device__ __forceinline__ unsigned xb_ld(unsigned* p)              { return __hip_atomic_load(p, __ATOMIC_RELAXED, __HIP_MEMORY_SCOPE_AGENT); }
; __device__ __forceinline__ unsigned xb_add(unsigned* p, unsigned v) { return __hip_atomic_fetch_add(p, v, __ATOMIC_RELAXED, __HIP_MEMORY_SCOPE_AGENT); }
; #define XB_SPIN(cond, bar) do { unsigned _sp = 0; while (cond) { __builtin_amdgcn_s_sleep(1); \
;     if ((++_sp & 255u) == 0u) { if (xb_ld(&(bar)[XB_TMO])) break; if (_sp > XB_SPIN_CAP) { atomicAdd(&(bar)[XB_TMO], 1u); break; } } } } while (0)
; __device__ __forceinline__ void xcd_barrier(const XcdBarrier& b) {
;     ...
;             const unsigned og = xb_add(&bar[XB_TOP], 1u);
;             const unsigned tg = og / nx;
;             const bool last_top = (og + 1u == (tg + 1u) * nx);
;             if (last_top) (void)__hip_atomic_fetch_add(&bar[XB_TOPGEN], 1u, __ATOMIC_RELAXED, __HIP_MEMORY_SCOPE_AGENT);
;             asm volatile("s_waitcnt vmcnt(0)" ::: "memory");
;             (void)__hip_atomic_fetch_add(&bar[XB_XGEN(b.x)], 1u, __ATOMIC_RELAXED, __HIP_MEMORY_SCOPE_AGENT);
;             if (!last_top) XB_SPIN(xb_ld(&bar[XB_TOPGEN]) == tg, bar);
.LBB0_742:
	s_or_b64 exec, exec, s[14:15]
	s_and_saveexec_b64 s[0:1], vcc
	s_cbranch_execz .LBB0_755
	v_mov_b32_e32 v2, 0x7000
	global_load_dword v2, v2, s[50:51] offset:1280 sc1
	s_add_u32 s12, s50, 0x7500
	s_addc_u32 s13, s51, 0
	s_waitcnt vmcnt(0)
	v_cmp_eq_u32_e32 vcc, v2, v3
	s_and_b64 vcc, vcc, exec
	s_cbranch_vccz .LBB0_755
	v_mov_b32_e32 v250, 0
	global_load_dword v244, v250, s[12:13] sc1
	s_sleep 14
	global_load_dword v246, v250, s[12:13] sc1
	s_sleep 14
	global_load_dword v248, v250, s[12:13] sc1
my_ll_4:
	s_waitcnt vmcnt(2)
	v_cmp_ne_u32_e32 vcc, v244, v3
	s_and_b64 vcc, vcc, exec
	s_cbranch_vccnz .LBB0_755
	global_load_dword v244, v250, s[12:13] sc1
	s_waitcnt vmcnt(2)
	v_cmp_ne_u32_e32 vcc, v246, v3
	s_and_b64 vcc, vcc, exec
	s_cbranch_vccnz .LBB0_755
	global_load_dword v246, v250, s[12:13] sc1
	s_waitcnt vmcnt(2)
	v_cmp_ne_u32_e32 vcc, v248, v3
	s_and_b64 vcc, vcc, exec
	s_cbranch_vccnz .LBB0_755
	global_load_dword v248, v250, s[12:13] sc1
	s_branch my_ll_4

; __device__ __forceinline__ unsigned xb_ld(unsigned* p)              { return __hip_atomic_load(p, __ATOMIC_RELAXED, __HIP_MEMORY_SCOPE_AGENT); }
; __device__ __forceinline__ void xcd_barrier(const XcdBarrier& b) {
;     ...
;             { unsigned _sp = 0; for (;;) { const unsigned a_ = xb_ld(&bar[XB_TOPGEN]), c_ = xb_ld(&bar[XB_XGEN(b.x)]); if (a_ != gen && c_ != gen) break; __builtin_amdgcn_s_sleep(1);
;                 if ((++_sp & 255u) == 0u) { if (xb_ld(&bar[XB_TMO])) break; if (_sp > XB_SPIN_CAP) { atomicAdd(&bar[XB_TMO], 1u); break; } } } }
my_pl_5:
	s_waitcnt vmcnt(4)
	v_cmp_ne_u32_e32 vcc, v244, v3
	v_cmp_ne_u32_e64 s[0:1], v245, v3
	s_and_b64 s[0:1], vcc, s[0:1]
	s_and_b64 s[0:1], s[0:1], exec
	s_cbranch_scc1 .LBB0_843
	global_load_dword v244, v250, s[16:17] sc1
	global_load_dword v245, v250, s[18:19] sc1
	s_waitcnt vmcnt(4)
	v_cmp_ne_u32_e32 vcc, v246, v3
	v_cmp_ne_u32_e64 s[0:1], v247, v3
	s_and_b64 s[0:1], vcc, s[0:1]
	s_and_b64 s[0:1], s[0:1], exec
	s_cbranch_scc1 .LBB0_843
	global_load_dword v246, v250, s[16:17] sc1
	global_load_dword v247, v250, s[18:19] sc1
	s_waitcnt vmcnt(4)
	v_cmp_ne_u32_e32 vcc, v248, v3
	v_cmp_ne_u32_e64 s[0:1], v249, v3
	s_and_b64 s[0:1], vcc, s[0:1]
	s_and_b64 s[0:1], s[0:1], exec
	s_cbranch_scc1 .LBB0_843
	global_load_dword v248, v250, s[16:17] sc1
	global_load_dword v249, v250, s[18:19] sc1
	s_branch my_pl_5

; __device__ __forceinline__ unsigned xb_ld(unsigned* p)              { return __hip_atomic_load(p, __ATOMIC_RELAXED, __HIP_MEMORY_SCOPE_AGENT); }
; #define XB_SPIN(cond, bar) do { unsigned _sp = 0; while (cond) { __builtin_amdgcn_s_sleep(1); \
;     if ((++_sp & 255u) == 0u) { if (xb_ld(&(bar)[XB_TMO])) break; if (_sp > XB_SPIN_CAP) { atomicAdd(&(bar)[XB_TMO], 1u); break; } } } } while (0)
; __device__ __forceinline__ void xcd_barrier(const XcdBarrier& b) {
;     ...
;             if (!last_top) XB_SPIN(xb_ld(&bar[XB_TOPGEN]) == tg, bar);
my_ll_5:
	s_waitcnt vmcnt(2)
	v_cmp_ne_u32_e32 vcc, v244, v3
	s_and_b64 vcc, vcc, exec
	s_cbranch_vccnz .LBB0_865
	global_load_dword v244, v250, s[10:11] sc1
	s_waitcnt vmcnt(2)
	v_cmp_ne_u32_e32 vcc, v246, v3
	s_and_b64 vcc, vcc, exec
	s_cbranch_vccnz .LBB0_865
	global_load_dword v246, v250, s[10:11] sc1
	s_waitcnt vmcnt(2)
	v_cmp_ne_u32_e32 vcc, v248, v3
	s_and_b64 vcc, vcc, exec
	s_cbranch_vccnz .LBB0_865
	global_load_dword v248, v250, s[10:11] sc1
	s_branch my_ll_5

; __device__ __forceinline__ unsigned xb_ld(unsigned* p)              { return __hip_atomic_load(p, __ATOMIC_RELAXED, __HIP_MEMORY_SCOPE_AGENT); }
; __device__ __forceinline__ void xcd_barrier(const XcdBarrier& b) {
;     ...
;             { unsigned _sp = 0; for (;;) { const unsigned a_ = xb_ld(&bar[XB_TOPGEN]), c_ = xb_ld(&bar[XB_XGEN(b.x)]); if (a_ != gen && c_ != gen) break; __builtin_amdgcn_s_sleep(1);
;                 if ((++_sp & 255u) == 0u) { if (xb_ld(&bar[XB_TMO])) break; if (_sp > XB_SPIN_CAP) { atomicAdd(&bar[XB_TMO], 1u); break; } } } }
my_pl_6:
	s_waitcnt vmcnt(4)
	v_cmp_ne_u32_e32 vcc, v244, v3
	v_cmp_ne_u32_e64 s[0:1], v245, v3
	s_and_b64 s[0:1], vcc, s[0:1]
	s_and_b64 s[0:1], s[0:1], exec
	s_cbranch_scc1 .LBB0_990
	global_load_dword v244, v250, s[16:17] sc1
	global_load_dword v245, v250, s[18:19] sc1
	s_waitcnt vmcnt(4)
	v_cmp_ne_u32_e32 vcc, v246, v3
	v_cmp_ne_u32_e64 s[0:1], v247, v3
	s_and_b64 s[0:1], vcc, s[0:1]
	s_and_b64 s[0:1], s[0:1], exec
	s_cbranch_scc1 .LBB0_990
	global_load_dword v246, v250, s[16:17] sc1
	global_load_dword v247, v250, s[18:19] sc1
	s_waitcnt vmcnt(4)
	v_cmp_ne_u32_e32 vcc, v248, v3
	v_cmp_ne_u32_e64 s[0:1], v249, v3
	s_and_b64 s[0:1], vcc, s[0:1]
	s_and_b64 s[0:1], s[0:1], exec
	s_cbranch_scc1 .LBB0_990
	global_load_dword v248, v250, s[16:17] sc1
	global_load_dword v249, v250, s[18:19] sc1
	s_branch my_pl_6

; __device__ __forceinline__ unsigned xb_ld(unsigned* p)              { return __hip_atomic_load(p, __ATOMIC_RELAXED, __HIP_MEMORY_SCOPE_AGENT); }
; #define XB_SPIN(cond, bar) do { unsigned _sp = 0; while (cond) { __builtin_amdgcn_s_sleep(1); \
;     if ((++_sp & 255u) == 0u) { if (xb_ld(&(bar)[XB_TMO])) break; if (_sp > XB_SPIN_CAP) { atomicAdd(&(bar)[XB_TMO], 1u); break; } } } } while (0)
; __device__ __forceinline__ void xcd_barrier(const XcdBarrier& b) {
;     ...
;             if (!last_top) XB_SPIN(xb_ld(&bar[XB_TOPGEN]) == tg, bar);
my_ll_6:
	s_waitcnt vmcnt(2)
	v_cmp_ne_u32_e32 vcc, v244, v3
	s_and_b64 vcc, vcc, exec
	s_cbranch_vccnz .LBB0_1012
	global_load_dword v244, v250, s[10:11] sc1
	s_waitcnt vmcnt(2)
	v_cmp_ne_u32_e32 vcc, v246, v3
	s_and_b64 vcc, vcc, exec
	s_cbranch_vccnz .LBB0_1012
	global_load_dword v246, v250, s[10:11] sc1
	s_waitcnt vmcnt(2)
	v_cmp_ne_u32_e32 vcc, v248, v3
	s_and_b64 vcc, vcc, exec
	s_cbranch_vccnz .LBB0_1012
	global_load_dword v248, v250, s[10:11] sc1
	s_branch my_ll_6

; __global__ void __launch_bounds__(NWAVES * 64, 2) mk_fwd(Args args) {
	.amdhsa_kernel _Z6mk_fwd4Args
		.amdhsa_group_segment_fixed_size 0
		.amdhsa_private_segment_fixed_size 0
		.amdhsa_kernarg_size 472
		.amdhsa_user_sgpr_count 2
		.amdhsa_user_sgpr_dispatch_ptr 0
		.amdhsa_user_sgpr_queue_ptr 0
		.amdhsa_user_sgpr_kernarg_segment_ptr 1
		.amdhsa_user_sgpr_dispatch_id 0
		.amdhsa_user_sgpr_kernarg_preload_length 0
		.amdhsa_user_sgpr_kernarg_preload_offset 0
		.amdhsa_user_sgpr_private_segment_size 0
		.amdhsa_uses_dynamic_stack 0
		.amdhsa_enable_private_segment 0
		.amdhsa_system_sgpr_workgroup_id_x 1
		.amdhsa_system_sgpr_workgroup_id_y 0
		.amdhsa_system_sgpr_workgroup_id_z 0
		.amdhsa_system_sgpr_workgroup_info 0
		.amdhsa_system_vgpr_workitem_id 0
		.amdhsa_next_free_vgpr 251
		.amdhsa_next_free_sgpr 98
		.amdhsa_accum_offset 252
		.amdhsa_reserve_vcc 1
		.amdhsa_float_round_mode_32 0
		.amdhsa_float_round_mode_16_64 0
		.amdhsa_float_denorm_mode_32 3
		.amdhsa_float_denorm_mode_16_64 3
		.amdhsa_dx10_clamp 1
		.amdhsa_ieee_mode 1
		.amdhsa_fp16_overflow 0
		.amdhsa_tg_split 0
		.amdhsa_exception_fp_ieee_invalid_op 0
		.amdhsa_exception_fp_denorm_src 0
		.amdhsa_exception_fp_ieee_div_zero 0
		.amdhsa_exception_fp_ieee_overflow 0
		.amdhsa_exception_fp_ieee_underflow 0
		.amdhsa_exception_fp_ieee_inexact 0
		.amdhsa_exception_int_div_zero 0
	.end_amdhsa_kernel

; __global__ void __launch_bounds__(NWAVES * 64, 2) mk_fwd(Args args) {
amdhsa.kernels:
  - .agpr_count:     0
    .args:
      - .offset:         0
        .size:           216
        .value_kind:     by_value
      - .offset:         216
        .size:           4
        .value_kind:     hidden_block_count_x
      - .offset:         220
        .size:           4
        .value_kind:     hidden_block_count_y
      - .offset:         224
        .size:           4
        .value_kind:     hidden_block_count_z
      - .offset:         228
        .size:           2
        .value_kind:     hidden_group_size_x
      - .offset:         230
        .size:           2
        .value_kind:     hidden_group_size_y
      - .offset:         232
        .size:           2
        .value_kind:     hidden_group_size_z
      - .offset:         234
        .size:           2
        .value_kind:     hidden_remainder_x
      - .offset:         236
        .size:           2
        .value_kind:     hidden_remainder_y
      - .offset:         238
        .size:           2
        .value_kind:     hidden_remainder_z
      - .offset:         256
        .size:           8
        .value_kind:     hidden_global_offset_x
      - .offset:         264
        .size:           8
        .value_kind:     hidden_global_offset_y
      - .offset:         272
        .size:           8
        .value_kind:     hidden_global_offset_z
      - .offset:         280
        .size:           2
        .value_kind:     hidden_grid_dims
      - .offset:         336
        .size:           4
        .value_kind:     hidden_dynamic_lds_size
    .group_segment_fixed_size: 0
    .kernarg_segment_align: 8
    .kernarg_segment_size: 472
    .language:       OpenCL C
    .language_version:
      - 2
      - 0
    .max_flat_workgroup_size: 512
    .name:           _Z6mk_fwd4Args
    .private_segment_fixed_size: 0
    .sgpr_count:     104
    .sgpr_spill_count: 71
    .symbol:         _Z6mk_fwd4Args.kd
    .uniform_work_group_size: 1
    .uses_dynamic_stack: false
    .vgpr_count:     251
    .vgpr_spill_count: 0
    .wavefront_size: 64
